# GEMM K loop: a single fragment wait (all twelve reads) before the first MFMA, no s_waitcnt inside the MFMA stream
# speedup vs baseline: 1.0006x; 1.0006x over previous
.LBB0_246:
	s_add_i32 s10, s7, 0xffffa000
	s_cmp_lg_u32 s7, 0
	s_cselect_b32 s12, s10, 0xc000
	v_add_u32_e32 v131, s7, v150
	s_waitcnt vmcnt(6)
	s_barrier
	v_add_u32_e32 v133, s7, v149
	ds_read_b128 v[154:157], v131 offset:0
	ds_read_b128 v[158:161], v131 offset:0x400
	ds_read_b128 v[162:165], v131 offset:0x800
	ds_read_b128 v[166:169], v131 offset:0xc00
	v_add_u32_e32 v131, s12, v147
	ds_read_b128 v[170:173], v133 offset:0
	ds_read_b128 v[174:177], v133 offset:0x400
	ds_read_b128 v[178:181], v133 offset:0x800
	ds_read_b128 v[200:203], v133 offset:0xc00
	ds_read_b128 v[204:207], v133 offset:0x1000
	ds_read_b128 v[208:211], v133 offset:0x1400
	ds_read_b128 v[212:215], v133 offset:0x1800
	ds_read_b128 v[216:219], v133 offset:0x1c00
	s_add_u32 s10, s8, s50
	s_addc_u32 s11, s9, s51
	v_readfirstlane_b32 s13, v131
	s_add_u32 s64, s5, s100
	s_addc_u32 s65, s6, 0
	s_add_i32 s66, s7, 0x6000
	s_cmpk_lg_u32 s7, 0xc000
	s_cselect_b32 s7, s66, 0
	s_addk_i32 s100, 0x400
	s_add_u32 s50, s50, s60
	s_addc_u32 s51, s51, 0
	s_sub_i32 s68, s13, s12
	s_lshr_b32 s68, s68, 1
	s_add_i32 s68, s68, s12
	s_addk_i32 s68, 0x4000
	s_waitcnt lgkmcnt(0)
	v_mfma_f32_16x16x32_bf16 v[126:129], v[154:157], v[170:173], v[126:129]
	v_mfma_f32_16x16x32_bf16 v[122:125], v[154:157], v[174:177], v[122:125]
	v_mfma_f32_16x16x32_bf16 v[118:121], v[154:157], v[178:181], v[118:121]
	v_mfma_f32_16x16x32_bf16 v[114:117], v[154:157], v[200:203], v[114:117]
	s_mov_b32 m0, s13
	v_mfma_f32_16x16x32_bf16 v[110:113], v[158:161], v[170:173], v[110:113]
	global_load_lds_dwordx4 v0, s[10:11]
	v_mfma_f32_16x16x32_bf16 v[102:105], v[158:161], v[174:177], v[102:105]
	v_mfma_f32_16x16x32_bf16 v[94:97], v[158:161], v[178:181], v[94:97]
	s_add_u32 m0, s13, 0x400
	v_mfma_f32_16x16x32_bf16 v[86:89], v[158:161], v[200:203], v[86:89]
	global_load_lds_dwordx4 v130, s[10:11]
	v_mfma_f32_16x16x32_bf16 v[78:81], v[162:165], v[170:173], v[78:81]
	v_mfma_f32_16x16x32_bf16 v[70:73], v[162:165], v[174:177], v[70:73]
	s_add_u32 m0, s13, 0x800
	v_mfma_f32_16x16x32_bf16 v[62:65], v[162:165], v[178:181], v[62:65]
	global_load_lds_dwordx4 v132, s[10:11]
	v_mfma_f32_16x16x32_bf16 v[54:57], v[162:165], v[200:203], v[54:57]
	v_mfma_f32_16x16x32_bf16 v[46:49], v[166:169], v[170:173], v[46:49]
	s_add_u32 m0, s13, 0xc00
	v_mfma_f32_16x16x32_bf16 v[38:41], v[166:169], v[174:177], v[38:41]
	global_load_lds_dwordx4 v136, s[10:11]
	v_mfma_f32_16x16x32_bf16 v[30:33], v[166:169], v[178:181], v[30:33]
	v_mfma_f32_16x16x32_bf16 v[22:25], v[166:169], v[200:203], v[22:25]
	v_mfma_f32_16x16x32_bf16 v[106:109], v[154:157], v[204:207], v[106:109]
	v_mfma_f32_16x16x32_bf16 v[98:101], v[154:157], v[208:211], v[98:101]
	s_mov_b32 m0, s68
	v_mfma_f32_16x16x32_bf16 v[90:93], v[154:157], v[212:215], v[90:93]
	global_load_lds_dwordx4 v138, s[64:65]
	v_mfma_f32_16x16x32_bf16 v[82:85], v[154:157], v[216:219], v[82:85]
	v_mfma_f32_16x16x32_bf16 v[74:77], v[158:161], v[204:207], v[74:77]
	v_mfma_f32_16x16x32_bf16 v[66:69], v[158:161], v[208:211], v[66:69]
	v_mfma_f32_16x16x32_bf16 v[58:61], v[158:161], v[212:215], v[58:61]
	v_mfma_f32_16x16x32_bf16 v[50:53], v[158:161], v[216:219], v[50:53]
	s_add_u32 m0, s68, 0x400
	v_mfma_f32_16x16x32_bf16 v[42:45], v[162:165], v[204:207], v[42:45]
	global_load_lds_dwordx4 v140, s[64:65]
	v_mfma_f32_16x16x32_bf16 v[34:37], v[162:165], v[208:211], v[34:37]
	v_mfma_f32_16x16x32_bf16 v[26:29], v[162:165], v[212:215], v[26:29]
	v_mfma_f32_16x16x32_bf16 v[18:21], v[162:165], v[216:219], v[18:21]
	v_mfma_f32_16x16x32_bf16 v[14:17], v[166:169], v[204:207], v[14:17]
	v_mfma_f32_16x16x32_bf16 v[10:13], v[166:169], v[208:211], v[10:13]
	v_mfma_f32_16x16x32_bf16 v[6:9], v[166:169], v[212:215], v[6:9]
	v_mfma_f32_16x16x32_bf16 v[2:5], v[166:169], v[216:219], v[2:5]
	s_cmpk_lg_i32 s100, 0x7800
	s_cbranch_scc1 .LBB0_246
	s_waitcnt vmcnt(6)
	s_barrier
	v_add_u32_e32 v0, s7, v150
	v_add_u32_e32 v140, s7, v149
	ds_read_b128 v[130:133], v0 offset:0
	ds_read_b128 v[136:139], v0 offset:0x400
	ds_read_b128 v[154:157], v0 offset:0x800
	ds_read_b128 v[158:161], v0 offset:0xc00
	ds_read_b128 v[162:165], v140 offset:0
	ds_read_b128 v[166:169], v140 offset:0x400
	ds_read_b128 v[170:173], v140 offset:0x800
	ds_read_b128 v[174:177], v140 offset:0xc00
	ds_read_b128 v[178:181], v140 offset:0x1000
	ds_read_b128 v[200:203], v140 offset:0x1400
	ds_read_b128 v[204:207], v140 offset:0x1800
	ds_read_b128 v[208:211], v140 offset:0x1c00
	s_lshl_b32 s49, s4, 8
	s_waitcnt lgkmcnt(4)
	s_nop 0
	v_mfma_f32_16x16x32_bf16 v[126:129], v[130:133], v[162:165], v[126:129]
	v_mfma_f32_16x16x32_bf16 v[118:121], v[130:133], v[170:173], v[118:121]
	v_mfma_f32_16x16x32_bf16 v[114:117], v[130:133], v[174:177], v[114:117]
	v_mfma_f32_16x16x32_bf16 v[110:113], v[136:139], v[162:165], v[110:113]
	v_mfma_f32_16x16x32_bf16 v[102:105], v[136:139], v[166:169], v[102:105]
	v_mfma_f32_16x16x32_bf16 v[94:97], v[136:139], v[170:173], v[94:97]
	v_mfma_f32_16x16x32_bf16 v[86:89], v[136:139], v[174:177], v[86:89]
	v_mfma_f32_16x16x32_bf16 v[70:73], v[154:157], v[166:169], v[70:73]
	v_mfma_f32_16x16x32_bf16 v[62:65], v[154:157], v[170:173], v[62:65]
	v_mfma_f32_16x16x32_bf16 v[54:57], v[154:157], v[174:177], v[54:57]
	v_mfma_f32_16x16x32_bf16 v[46:49], v[158:161], v[162:165], v[46:49]
	v_mfma_f32_16x16x32_bf16 v[38:41], v[158:161], v[166:169], v[38:41]
	v_mfma_f32_16x16x32_bf16 v[30:33], v[158:161], v[170:173], v[30:33]
	v_mfma_f32_16x16x32_bf16 v[22:25], v[158:161], v[174:177], v[22:25]
	v_mfma_f32_16x16x32_bf16 v[212:215], v[130:133], v[166:169], v[122:125]
	v_mfma_f32_16x16x32_bf16 v[216:219], v[154:157], v[162:165], v[78:81]
	s_waitcnt lgkmcnt(0)
	s_nop 0
	v_mfma_f32_16x16x32_bf16 v[174:177], v[136:139], v[178:181], v[74:77]
	v_mfma_f32_16x16x32_bf16 v[220:223], v[136:139], v[200:203], v[66:69]
	v_mfma_f32_16x16x32_bf16 v[224:227], v[136:139], v[204:207], v[58:61]
	v_mfma_f32_16x16x32_bf16 v[50:53], v[136:139], v[208:211], v[50:53]
	v_mfma_f32_16x16x32_bf16 v[136:139], v[154:157], v[178:181], v[42:45]
	v_mfma_f32_16x16x32_bf16 v[34:37], v[154:157], v[200:203], v[34:37]
	v_mfma_f32_16x16x32_bf16 v[6:9], v[158:161], v[204:207], v[6:9]
	v_mfma_f32_16x16x32_bf16 v[162:165], v[130:133], v[178:181], v[106:109]
	v_mfma_f32_16x16x32_bf16 v[166:169], v[130:133], v[200:203], v[98:101]
	v_mfma_f32_16x16x32_bf16 v[170:173], v[130:133], v[204:207], v[90:93]
	v_mfma_f32_16x16x32_bf16 v[130:133], v[130:133], v[208:211], v[82:85]
	v_mfma_f32_16x16x32_bf16 v[228:231], v[154:157], v[204:207], v[26:29]
	v_mfma_f32_16x16x32_bf16 v[154:157], v[154:157], v[208:211], v[18:21]
	v_mfma_f32_16x16x32_bf16 v[178:181], v[158:161], v[178:181], v[14:17]
	v_mfma_f32_16x16x32_bf16 v[200:203], v[158:161], v[200:203], v[10:13]
	v_mfma_f32_16x16x32_bf16 v[158:161], v[158:161], v[208:211], v[2:5]
	s_waitcnt vmcnt(0)
	s_barrier
	ds_read_b128 v[2:5], v151 offset:0
	ds_read_b128 v[14:17], v151 offset:0x400
	ds_read_b128 v[204:207], v151 offset:0x800
	ds_read_b128 v[208:211], v151 offset:0xc00
	ds_read_b128 v[10:13], v152 offset:0
	ds_read_b128 v[18:21], v152 offset:0x400
	ds_read_b128 v[26:29], v152 offset:0x800
	ds_read_b128 v[42:45], v152 offset:0xc00
	ds_read_b128 v[232:235], v152 offset:0x1000
	ds_read_b128 v[236:239], v152 offset:0x1400
	ds_read_b128 v[240:243], v152 offset:0x1800
	ds_read_b128 v[244:247], v152 offset:0x1c00
	s_nop 0
	s_waitcnt lgkmcnt(4)
	s_nop 0
	v_mfma_f32_16x16x32_bf16 v[122:125], v[2:5], v[10:13], v[126:129]
	v_mfma_f32_16x16x32_bf16 v[106:109], v[2:5], v[18:21], v[212:215]
	v_mfma_f32_16x16x32_bf16 v[90:93], v[2:5], v[26:29], v[118:121]
	v_mfma_f32_16x16x32_bf16 v[74:77], v[2:5], v[42:45], v[114:117]
	v_mfma_f32_16x16x32_bf16 v[126:129], v[14:17], v[10:13], v[110:113]
	v_mfma_f32_16x16x32_bf16 v[110:113], v[14:17], v[18:21], v[102:105]
	v_mfma_f32_16x16x32_bf16 v[94:97], v[14:17], v[26:29], v[94:97]
	v_mfma_f32_16x16x32_bf16 v[78:81], v[14:17], v[42:45], v[86:89]
	v_mfma_f32_16x16x32_bf16 v[114:117], v[204:207], v[10:13], v[216:219]
	v_mfma_f32_16x16x32_bf16 v[98:101], v[204:207], v[18:21], v[70:73]
	v_mfma_f32_16x16x32_bf16 v[82:85], v[204:207], v[26:29], v[62:65]
	v_mfma_f32_16x16x32_bf16 v[66:69], v[204:207], v[42:45], v[54:57]
	v_mfma_f32_16x16x32_bf16 v[118:121], v[208:211], v[10:13], v[46:49]
	v_mfma_f32_16x16x32_bf16 v[102:105], v[208:211], v[18:21], v[38:41]
	v_mfma_f32_16x16x32_bf16 v[86:89], v[208:211], v[26:29], v[30:33]
	v_mfma_f32_16x16x32_bf16 v[70:73], v[208:211], v[42:45], v[22:25]
	s_waitcnt lgkmcnt(0)
	s_nop 0
	v_mfma_f32_16x16x32_bf16 v[58:61], v[2:5], v[232:235], v[162:165]
	v_mfma_f32_16x16x32_bf16 v[42:45], v[2:5], v[236:239], v[166:169]
	v_mfma_f32_16x16x32_bf16 v[26:29], v[2:5], v[240:243], v[170:173]
	v_mfma_f32_16x16x32_bf16 v[10:13], v[2:5], v[244:247], v[130:133]
	v_mfma_f32_16x16x32_bf16 v[62:65], v[14:17], v[232:235], v[174:177]
	v_mfma_f32_16x16x32_bf16 v[46:49], v[14:17], v[236:239], v[220:223]
	v_mfma_f32_16x16x32_bf16 v[30:33], v[14:17], v[240:243], v[224:227]
	v_mfma_f32_16x16x32_bf16 v[14:17], v[14:17], v[244:247], v[50:53]
	v_mfma_f32_16x16x32_bf16 v[50:53], v[204:207], v[232:235], v[136:139]
	v_mfma_f32_16x16x32_bf16 v[34:37], v[204:207], v[236:239], v[34:37]
	v_mfma_f32_16x16x32_bf16 v[18:21], v[204:207], v[240:243], v[228:231]
	v_mfma_f32_16x16x32_bf16 v[2:5], v[204:207], v[244:247], v[154:157]
	v_mfma_f32_16x16x32_bf16 v[54:57], v[208:211], v[232:235], v[178:181]
	v_mfma_f32_16x16x32_bf16 v[38:41], v[208:211], v[236:239], v[200:203]
	v_mfma_f32_16x16x32_bf16 v[22:25], v[208:211], v[240:243], v[6:9]
	v_mfma_f32_16x16x32_bf16 v[6:9], v[208:211], v[244:247], v[158:161]
	v_mov_b32_e32 v136, v134
	s_mov_b64 s[50:51], -1
	s_and_b64 vcc, exec, s[22:23]
	s_barrier
	s_cbranch_vccz .LBB0_264
	s_and_b64 vcc, exec, s[0:1]
	s_cbranch_vccz .LBB0_250
	v_lshrrev_b32_e32 v0, 6, v136
	v_mul_lo_u32 v137, v0, s14
	v_and_b32_e32 v130, 15, v136
	v_and_or_b32 v0, v136, 48, v137
	s_movk_i32 s4, 0x90
	v_mad_u32_u24 v0, v130, s4, v0
	v_cvt_pk_bf16_f32 v130, v122, v123
	v_cvt_pk_bf16_f32 v131, v124, v125
	v_cvt_pk_bf16_f32 v132, v126, v127
	v_cvt_pk_bf16_f32 v133, v128, v129
	s_waitcnt vmcnt(0)
	ds_write_b128 v0, v[130:133]
	v_cvt_pk_bf16_f32 v130, v114, v115
	v_cvt_pk_bf16_f32 v131, v116, v117
	v_cvt_pk_bf16_f32 v132, v118, v119
	v_cvt_pk_bf16_f32 v133, v120, v121
	ds_write_b128 v0, v[130:133] offset:64
	v_cvt_pk_bf16_f32 v130, v106, v107
	v_cvt_pk_bf16_f32 v131, v108, v109
	v_cvt_pk_bf16_f32 v132, v110, v111
	v_cvt_pk_bf16_f32 v133, v112, v113
	ds_write_b128 v0, v[130:133] offset:2304
	v_cvt_pk_bf16_f32 v130, v98, v99
	v_cvt_pk_bf16_f32 v131, v100, v101
	v_cvt_pk_bf16_f32 v132, v102, v103
	v_cvt_pk_bf16_f32 v133, v104, v105
	ds_write_b128 v0, v[130:133] offset:2368
	v_cvt_pk_bf16_f32 v130, v90, v91
	v_cvt_pk_bf16_f32 v131, v92, v93
	v_cvt_pk_bf16_f32 v132, v94, v95
	v_cvt_pk_bf16_f32 v133, v96, v97
	ds_write_b128 v0, v[130:133] offset:4608
	v_cvt_pk_bf16_f32 v130, v82, v83
	v_cvt_pk_bf16_f32 v131, v84, v85
	v_cvt_pk_bf16_f32 v132, v86, v87
	v_cvt_pk_bf16_f32 v133, v88, v89
	ds_write_b128 v0, v[130:133] offset:4672
	v_cvt_pk_bf16_f32 v130, v74, v75
	v_cvt_pk_bf16_f32 v131, v76, v77
	v_cvt_pk_bf16_f32 v132, v78, v79
	v_cvt_pk_bf16_f32 v133, v80, v81
	ds_write_b128 v0, v[130:133] offset:6912
	v_cvt_pk_bf16_f32 v130, v66, v67
	v_cvt_pk_bf16_f32 v131, v68, v69
	v_cvt_pk_bf16_f32 v132, v70, v71
	v_cvt_pk_bf16_f32 v133, v72, v73
	ds_write_b128 v0, v[130:133] offset:6976
	v_cvt_pk_bf16_f32 v130, v58, v59
	v_cvt_pk_bf16_f32 v131, v60, v61
	v_cvt_pk_bf16_f32 v132, v62, v63
	v_cvt_pk_bf16_f32 v133, v64, v65
	ds_write_b128 v0, v[130:133] offset:9216
	v_cvt_pk_bf16_f32 v130, v50, v51
	v_cvt_pk_bf16_f32 v131, v52, v53
	v_cvt_pk_bf16_f32 v132, v54, v55
	v_cvt_pk_bf16_f32 v133, v56, v57
	ds_write_b128 v0, v[130:133] offset:9280
	v_cvt_pk_bf16_f32 v130, v42, v43
	v_cvt_pk_bf16_f32 v131, v44, v45
	v_cvt_pk_bf16_f32 v132, v46, v47
	v_cvt_pk_bf16_f32 v133, v48, v49
	ds_write_b128 v0, v[130:133] offset:11520
	v_cvt_pk_bf16_f32 v130, v34, v35
	v_cvt_pk_bf16_f32 v131, v36, v37
	v_cvt_pk_bf16_f32 v132, v38, v39
	v_cvt_pk_bf16_f32 v133, v40, v41
	ds_write_b128 v0, v[130:133] offset:11584
	v_cvt_pk_bf16_f32 v130, v26, v27
	v_cvt_pk_bf16_f32 v131, v28, v29
	v_cvt_pk_bf16_f32 v132, v30, v31
	v_cvt_pk_bf16_f32 v133, v32, v33
	ds_write_b128 v0, v[130:133] offset:13824
	v_cvt_pk_bf16_f32 v130, v18, v19
	v_cvt_pk_bf16_f32 v131, v20, v21
	v_cvt_pk_bf16_f32 v132, v22, v23
	v_cvt_pk_bf16_f32 v133, v24, v25
	ds_write_b128 v0, v[130:133] offset:13888
	v_cvt_pk_bf16_f32 v130, v10, v11
	v_cvt_pk_bf16_f32 v131, v12, v13
	v_cvt_pk_bf16_f32 v132, v14, v15
	v_cvt_pk_bf16_f32 v133, v16, v17
	ds_write_b128 v0, v[130:133] offset:16128
	v_cvt_pk_bf16_f32 v130, v2, v3
	v_cvt_pk_bf16_f32 v131, v4, v5
	v_cvt_pk_bf16_f32 v132, v6, v7
	v_cvt_pk_bf16_f32 v133, v8, v9
	ds_write_b128 v0, v[130:133] offset:16192
	v_and_b32_e32 v0, 0xffffff80, v136
	v_add_u32_e32 v130, s48, v0
	v_ashrrev_i32_e32 v131, 31, v130
	v_lshlrev_b64 v[130:131], 11, v[130:131]
	v_lshl_add_u64 v[130:131], s[38:39], 0, v[130:131]
	v_and_b32_e32 v0, 64, v136
	v_lshl_add_u64 v[130:131], s[46:47], 1, v[130:131]
	v_lshlrev_b32_e32 v0, 1, v0
	v_lshl_add_u64 v[138:139], v[130:131], 0, v[0:1]
	v_lshlrev_b32_e32 v0, 4, v136
	v_and_b32_e32 v0, 0x70, v0
	v_bfe_u32 v140, v136, 3, 3
	v_or_b32_e32 v130, v137, v0
	s_waitcnt lgkmcnt(0)
	v_mad_u32_u24 v137, v140, s4, v130
	ds_read_b128 v[66:69], v137
	ds_read_b128 v[70:73], v137 offset:1152
	ds_read_b128 v[74:77], v137 offset:2304
	ds_read_b128 v[78:81], v137 offset:3456
	ds_read_b128 v[82:85], v137 offset:4608
	ds_read_b128 v[86:89], v137 offset:5760
	ds_read_b128 v[90:93], v137 offset:6912
	ds_read_b128 v[94:97], v137 offset:8064
	ds_read_b128 v[98:101], v137 offset:9216
	ds_read_b128 v[102:105], v137 offset:10368
	ds_read_b128 v[106:109], v137 offset:11520
	ds_read_b128 v[110:113], v137 offset:12672
	ds_read_b128 v[114:117], v137 offset:13824
	ds_read_b128 v[118:121], v137 offset:14976
	ds_read_b128 v[122:125], v137 offset:16128
	ds_read_b128 v[126:129], v137 offset:17280
	v_lshl_add_u64 v[138:139], v[138:139], 0, v[0:1]
	v_lshlrev_b32_e32 v0, 11, v140
	v_lshl_add_u64 v[140:141], v[138:139], 0, v[0:1]
	s_mov_b64 s[50:51], 0
	s_waitcnt lgkmcnt(15)
	global_store_dwordx4 v[140:141], v[66:69], off
	v_or_b32_e32 v140, 0x4000, v0
	v_mov_b32_e32 v141, v1
	v_lshl_add_u64 v[140:141], v[138:139], 0, v[140:141]
	s_waitcnt lgkmcnt(14)
	global_store_dwordx4 v[140:141], v[70:73], off
	v_or_b32_e32 v140, 0x8000, v0
	v_mov_b32_e32 v141, v1
	v_lshl_add_u64 v[140:141], v[138:139], 0, v[140:141]
	s_waitcnt lgkmcnt(13)
	global_store_dwordx4 v[140:141], v[74:77], off
	v_or_b32_e32 v140, 0xc000, v0
	v_mov_b32_e32 v141, v1
	v_lshl_add_u64 v[140:141], v[138:139], 0, v[140:141]
	s_waitcnt lgkmcnt(12)
	global_store_dwordx4 v[140:141], v[78:81], off
	v_or_b32_e32 v140, 0x10000, v0
	v_mov_b32_e32 v141, v1
	v_lshl_add_u64 v[140:141], v[138:139], 0, v[140:141]
	s_waitcnt lgkmcnt(11)
	global_store_dwordx4 v[140:141], v[82:85], off
	v_or_b32_e32 v140, 0x14000, v0
	v_mov_b32_e32 v141, v1
	v_lshl_add_u64 v[140:141], v[138:139], 0, v[140:141]
	s_waitcnt lgkmcnt(10)
	global_store_dwordx4 v[140:141], v[86:89], off
	v_or_b32_e32 v140, 0x18000, v0
	v_mov_b32_e32 v141, v1
	v_lshl_add_u64 v[140:141], v[138:139], 0, v[140:141]
	s_waitcnt lgkmcnt(9)
	global_store_dwordx4 v[140:141], v[90:93], off
	v_or_b32_e32 v140, 0x1c000, v0
	v_mov_b32_e32 v141, v1
	v_lshl_add_u64 v[140:141], v[138:139], 0, v[140:141]
	s_waitcnt lgkmcnt(8)
	global_store_dwordx4 v[140:141], v[94:97], off
	v_or_b32_e32 v140, 0x20000, v0
	v_mov_b32_e32 v141, v1
	v_lshl_add_u64 v[140:141], v[138:139], 0, v[140:141]
	s_waitcnt lgkmcnt(7)
	global_store_dwordx4 v[140:141], v[98:101], off
	v_or_b32_e32 v140, 0x24000, v0
	v_mov_b32_e32 v141, v1
	v_lshl_add_u64 v[140:141], v[138:139], 0, v[140:141]
	s_waitcnt lgkmcnt(6)
	global_store_dwordx4 v[140:141], v[102:105], off
	v_or_b32_e32 v140, 0x28000, v0
	v_mov_b32_e32 v141, v1
	v_lshl_add_u64 v[140:141], v[138:139], 0, v[140:141]
	s_waitcnt lgkmcnt(5)
	global_store_dwordx4 v[140:141], v[106:109], off
	v_or_b32_e32 v140, 0x2c000, v0
	v_mov_b32_e32 v141, v1
	v_lshl_add_u64 v[140:141], v[138:139], 0, v[140:141]
	s_waitcnt lgkmcnt(4)
	global_store_dwordx4 v[140:141], v[110:113], off
	v_or_b32_e32 v140, 0x30000, v0
	v_mov_b32_e32 v141, v1
	v_lshl_add_u64 v[140:141], v[138:139], 0, v[140:141]
	s_waitcnt lgkmcnt(3)
	global_store_dwordx4 v[140:141], v[114:117], off
	v_or_b32_e32 v140, 0x34000, v0
	v_mov_b32_e32 v141, v1
	v_lshl_add_u64 v[140:141], v[138:139], 0, v[140:141]
	s_waitcnt lgkmcnt(2)
	global_store_dwordx4 v[140:141], v[118:121], off
	v_or_b32_e32 v140, 0x38000, v0
	v_mov_b32_e32 v141, v1
	v_lshl_add_u64 v[140:141], v[138:139], 0, v[140:141]
	v_or_b32_e32 v0, 0x3c000, v0
	s_waitcnt lgkmcnt(1)
	global_store_dwordx4 v[140:141], v[122:125], off
	v_lshl_add_u64 v[138:139], v[138:139], 0, v[0:1]
	s_waitcnt lgkmcnt(0)
	global_store_dwordx4 v[138:139], v[126:129], off
	s_waitcnt lgkmcnt(0)
	s_barrier
